# combo13 + final RMSNorm phase: all of a unit's x blocks and row sum-of-squares pairs requested at the top of the unit (one memory round trip instead of 16)
# baseline (speedup 1.0000x reference)
; #define GAS __attribute__((address_space(1)))
; __device__ __forceinline__ float rowss_sum(const float* p8) { const f32x4 a = *(const GAS f32x4*)((const GAS float*)p8), b = *(const GAS f32x4*)((const GAS float*)p8 + 4); return ((a[0] + a[1]) + (a[2] + a[3])) + ((b[0] + b[1]) + (b[2] + b[3])); }
;     __device__ __forceinline__ bool next(int i, Unit& u) const { const int off = i * H + (r >> 1); if (off >= 8 * nN) return false; u.pm = 16 * g + 8 * (r & 1) + (off & 7); u.pn = off >> 3; return true; }
; __device__ __forceinline__ void phase_final(const float* X, const float* rowss, const float* g, float* out, int grp, int rank, int H, int wv) {
;     ...
;     for (int i = 0; S.next(i, u); ++i) {
;         const GAS char* xb = (const GAS char*)X + ((size_t)(u.pm * 8 + u.pn) * 8 + wid) * (X_BF16 ? 16384 : 32768) + lane * 16;
;         const int row0 = u.pm * 256 + wr * 64 + fr, col0 = u.pn * 256 + wc * 32 + 8 * fq;
;         f32x4 gv[2][2];
; #pragma unroll
;         for (int bj = 0; bj < 2; ++bj)
; #pragma unroll
;             for (int n = 0; n < 2; ++n) gv[bj][n] = *(const GAS f32x4*)((const GAS float*)g + col0 + bj * 128 + n * 4);
; #pragma unroll
;         for (int h = 0; h < 2; ++h)
; #pragma unroll
;             for (int m = 0; m < 4; ++m) {
;                 const int row = row0 + h * 128 + m * 16;
;                 const float rs = __builtin_amdgcn_rsqf(rowss_sum(rowss + (size_t)row * 8) * INV_D + EPS);
;                 GAS float* orow = (GAS float*)out + (size_t)row * D + col0;
; #pragma unroll
;                 for (int bj = 0; bj < 2; ++bj) {
;     ...
;                     const u32x4 q = *(const GAS u32x4*)(xb + (size_t)((h * 4 + m) * 2 + bj) * 1024);
.LBB0_1446:
	s_and_b32 s6, s6, 7
	v_lshl_or_b32 v0, s66, 8, v36
	s_or_b32 s6, s6, s15
	v_ashrrev_i32_e32 v1, 31, v0
	v_lshlrev_b64 v[0:1], 2, v[0:1]
	v_lshl_add_u32 v20, s6, 8, v37
	v_lshl_add_u64 v[22:23], s[0:1], 0, v[0:1]
	v_ashrrev_i32_e32 v21, 31, v20
	v_lshl_add_u64 v[18:19], s[2:3], 0, v[0:1]
	global_load_dwordx4 v[8:11], v[22:23], off offset:16
	global_load_dwordx4 v[12:15], v[22:23], off
	global_load_dwordx4 v[0:3], v[22:23], off offset:528
	global_load_dwordx4 v[4:7], v[22:23], off offset:512
	v_lshlrev_b64 v[22:23], 5, v[20:21]
	v_lshlrev_b64 v[40:41], 13, v[20:21]
	v_lshl_add_u64 v[22:23], s[4:5], 0, v[22:23]
	s_lshl_b32 s7, s6, 3
	v_lshl_add_u64 v[52:53], v[18:19], 0, v[40:41]
	global_load_dwordx4 v[40:43], v[22:23], off
	global_load_dwordx4 v[44:47], v[22:23], off offset:16
	s_add_i32 s6, s7, s66
	v_or_b32_e32 v24, 16, v20
	v_or_b32_e32 v26, 32, v20
	s_ashr_i32 s7, s6, 31
	v_ashrrev_i32_e32 v25, 31, v24
	v_ashrrev_i32_e32 v27, 31, v26
	s_lshl_b64 s[6:7], s[6:7], 17
	v_lshlrev_b64 v[48:49], 5, v[24:25]
	v_lshlrev_b64 v[50:51], 5, v[26:27]
	v_lshlrev_b64 v[54:55], 13, v[26:27]
	v_lshl_add_u64 v[26:27], v[16:17], 0, s[6:7]
	v_lshl_add_u64 v[66:67], s[4:5], 0, v[48:49]
	v_lshl_add_u64 v[70:71], s[4:5], 0, v[50:51]
	global_load_dwordx4 v[48:51], v[26:27], off
	v_add_u32_e32 v34, 0x90, v20
	v_ashrrev_i32_e32 v35, 31, v34
	v_lshlrev_b64 v[24:25], 13, v[24:25]
	v_lshlrev_b64 v[62:63], 13, v[34:35]
	v_lshl_add_u64 v[68:69], v[18:19], 0, v[24:25]
	v_lshl_add_u64 v[24:25], v[18:19], 0, v[62:63]
	v_add_u32_e32 v32, 0x80, v20
	v_ashrrev_i32_e32 v33, 31, v32
	v_or_b32_e32 v30, 48, v20
	v_lshlrev_b64 v[58:59], 5, v[32:33]
	v_lshlrev_b64 v[32:33], 13, v[32:33]
	v_lshlrev_b64 v[60:61], 5, v[34:35]
	v_ashrrev_i32_e32 v31, 31, v30
	v_lshl_add_u64 v[34:35], v[18:19], 0, v[32:33]
	v_lshl_add_u64 v[32:33], s[4:5], 0, v[60:61]
	v_add_co_u32_e32 v60, vcc, s9, v26
	v_lshlrev_b64 v[56:57], 5, v[30:31]
	v_lshlrev_b64 v[30:31], 13, v[30:31]
	v_addc_co_u32_e32 v61, vcc, 0, v27, vcc
	v_lshl_add_u64 v[72:73], v[18:19], 0, v[30:31]
	v_add_co_u32_e32 v30, vcc, s10, v26
	v_lshl_add_u64 v[54:55], v[18:19], 0, v[54:55]
	s_nop 0
	v_addc_co_u32_e32 v31, vcc, 0, v27, vcc
	v_lshl_add_u64 v[56:57], s[4:5], 0, v[56:57]
	v_lshl_add_u64 v[58:59], s[4:5], 0, v[58:59]
	v_add_u32_e32 v28, 0xa0, v20
	v_ashrrev_i32_e32 v29, 31, v28
	v_lshlrev_b64 v[64:65], 5, v[28:29]
	v_lshl_add_u64 v[22:23], s[4:5], 0, v[64:65]
	s_add_i32 s8, s8, 1
	s_add_i32 s12, s13, s12
	s_mul_i32 s6, s8, s13
	s_add_i32 s6, s6, s14
	s_ashr_i32 s66, s12, 3
	s_cmp_lt_i32 s12, 64
	v_add_co_u32_e32 v228, vcc, s11, v26
	s_nop 0
	v_addc_co_u32_e32 v229, vcc, 0, v27, vcc
	global_load_dwordx4 v[104:107], v[26:27], off offset:1024
	global_load_dwordx4 v[172:175], v[66:67], off
	global_load_dwordx4 v[176:179], v[66:67], off offset:16
	global_load_dwordx4 v[108:111], v[26:27], off offset:2048
	global_load_dwordx4 v[112:115], v[26:27], off offset:3072
	global_load_dwordx4 v[180:183], v[70:71], off
	global_load_dwordx4 v[184:187], v[70:71], off offset:16
	global_load_dwordx4 v[116:119], v[60:61], off
	global_load_dwordx4 v[120:123], v[60:61], off offset:1024
	global_load_dwordx4 v[188:191], v[56:57], off
	global_load_dwordx4 v[192:195], v[56:57], off offset:16
	global_load_dwordx4 v[124:127], v[60:61], off offset:2048
	global_load_dwordx4 v[128:131], v[60:61], off offset:3072
	global_load_dwordx4 v[196:199], v[58:59], off
	global_load_dwordx4 v[200:203], v[58:59], off offset:16
	global_load_dwordx4 v[132:135], v[30:31], off
	global_load_dwordx4 v[136:139], v[30:31], off offset:1024
	global_load_dwordx4 v[204:207], v[58:59], off offset:512
	global_load_dwordx4 v[208:211], v[58:59], off offset:528
	global_load_dwordx4 v[140:143], v[30:31], off offset:2048
	global_load_dwordx4 v[144:147], v[30:31], off offset:3072
	global_load_dwordx4 v[212:215], v[58:59], off offset:1024
	global_load_dwordx4 v[216:219], v[58:59], off offset:1040
	global_load_dwordx4 v[148:151], v[228:229], off
	global_load_dwordx4 v[152:155], v[228:229], off offset:1024
	global_load_dwordx4 v[220:223], v[58:59], off offset:1536
	global_load_dwordx4 v[224:227], v[58:59], off offset:1552
	global_load_dwordx4 v[156:159], v[228:229], off offset:2048
	global_load_dwordx4 v[160:163], v[228:229], off offset:3072
	s_waitcnt vmcnt(0)
; #define GAS __attribute__((address_space(1)))
; __device__ __forceinline__ float bf_lo(unsigned w) { return __uint_as_float(w << 16); }
; __device__ __forceinline__ float bf_hi(unsigned w) { return __uint_as_float(w & 0xffff0000u); }
; __device__ __forceinline__ float rowss_sum(const float* p8) { const f32x4 a = *(const GAS f32x4*)((const GAS float*)p8), b = *(const GAS f32x4*)((const GAS float*)p8 + 4); return ((a[0] + a[1]) + (a[2] + a[3])) + ((b[0] + b[1]) + (b[2] + b[3])); }
; __device__ __forceinline__ void phase_final(const float* X, const float* rowss, const float* g, float* out, int grp, int rank, int H, int wv) {
;     ...
; #pragma unroll
;         for (int h = 0; h < 2; ++h)
; #pragma unroll
;             for (int m = 0; m < 4; ++m) {
;                 const int row = row0 + h * 128 + m * 16;
;                 const float rs = __builtin_amdgcn_rsqf(rowss_sum(rowss + (size_t)row * 8) * INV_D + EPS);
;                 GAS float* orow = (GAS float*)out + (size_t)row * D + col0;
; #pragma unroll
;                 for (int bj = 0; bj < 2; ++bj) {
;     ...
;                     const u32x4 q = *(const GAS u32x4*)(xb + (size_t)((h * 4 + m) * 2 + bj) * 1024);
;                     f32x4 v0, v1;
;                     if (X_BF16 == 2) x20_unpack(q, *(const GAS unsigned*)((const GAS char*)X + (WS_XL - WS_X) + ((size_t)(u.pm * 8 + u.pn) * 8 + wid) * 4096 + (size_t)((h * 4 + m) * 2 + bj) * 256 + lane * 4), v0, v1);
;                     else if (X_BF16 == 3) xh_unpack(q, v0, v1);
;                     else { v0 = (f32x4){bf_lo(q.x), bf_hi(q.x), bf_lo(q.y), bf_hi(q.y)}; v1 = (f32x4){bf_lo(q.z), bf_hi(q.z), bf_lo(q.w), bf_hi(q.w)}; }
;                     *(GAS f32x4*)(orow + bj * 128) = v0 * rs * gv[bj][0]; *(GAS f32x4*)(orow + bj * 128 + 4) = v1 * rs * gv[bj][1];
	v_mov_b32_e32 v62, v40
	v_mov_b32_e32 v63, v44
	v_mov_b32_e32 v44, v41
	v_mov_b32_e32 v40, v42
	v_mov_b32_e32 v41, v46
	v_mov_b32_e32 v46, v43
	v_pk_add_f32 v[42:43], v[62:63], v[44:45]
	v_pk_add_f32 v[40:41], v[40:41], v[46:47]
	v_cvt_f32_f16_e32 v44, v48
	v_pk_add_f32 v[40:41], v[42:43], v[40:41]
	v_cvt_f32_f16_sdwa v45, v48 dst_sel:DWORD dst_unused:UNUSED_PAD src0_sel:WORD_1
	v_add_f32_e32 v21, v40, v41
	v_fmamk_f32 v21, v21, 0x3a000000, v38
	v_cvt_f32_f16_e32 v46, v49
	v_cvt_f32_f16_sdwa v47, v49 dst_sel:DWORD dst_unused:UNUSED_PAD src0_sel:WORD_1
	v_rsq_f32_e32 v62, v21
	v_cvt_f32_f16_e32 v48, v50
	v_cvt_f32_f16_sdwa v49, v50 dst_sel:DWORD dst_unused:UNUSED_PAD src0_sel:WORD_1
	v_cvt_f32_f16_e32 v50, v51
	v_cvt_f32_f16_sdwa v51, v51 dst_sel:DWORD dst_unused:UNUSED_PAD src0_sel:WORD_1
	v_pk_mul_f32 v[40:41], v[44:45], v[62:63] op_sel_hi:[1,0]
	v_pk_mul_f32 v[42:43], v[46:47], v[62:63] op_sel_hi:[1,0]
	v_pk_mul_f32 v[44:45], v[48:49], v[62:63] op_sel_hi:[1,0]
	v_pk_mul_f32 v[46:47], v[50:51], v[62:63] op_sel_hi:[1,0]
	v_pk_mul_f32 v[42:43], v[14:15], v[42:43]
	v_pk_mul_f32 v[40:41], v[12:13], v[40:41]
	v_pk_mul_f32 v[46:47], v[10:11], v[46:47]
	v_pk_mul_f32 v[44:45], v[8:9], v[44:45]
	global_store_dwordx4 v[52:53], v[40:43], off
	global_store_dwordx4 v[52:53], v[44:47], off offset:16
	s_nop 1
	v_mov_b32_e32 v40, v104
	v_mov_b32_e32 v41, v105
	v_mov_b32_e32 v42, v106
	v_mov_b32_e32 v43, v107
	v_cvt_f32_f16_e32 v44, v40
	v_cvt_f32_f16_sdwa v45, v40 dst_sel:DWORD dst_unused:UNUSED_PAD src0_sel:WORD_1
	v_cvt_f32_f16_e32 v40, v41
	v_cvt_f32_f16_sdwa v41, v41 dst_sel:DWORD dst_unused:UNUSED_PAD src0_sel:WORD_1
	v_cvt_f32_f16_e32 v46, v42
	v_cvt_f32_f16_sdwa v47, v42 dst_sel:DWORD dst_unused:UNUSED_PAD src0_sel:WORD_1
	v_cvt_f32_f16_e32 v42, v43
	v_cvt_f32_f16_sdwa v43, v43 dst_sel:DWORD dst_unused:UNUSED_PAD src0_sel:WORD_1
	v_pk_mul_f32 v[44:45], v[62:63], v[44:45] op_sel_hi:[0,1]
	v_pk_mul_f32 v[40:41], v[62:63], v[40:41] op_sel_hi:[0,1]
	v_pk_mul_f32 v[48:49], v[62:63], v[46:47] op_sel_hi:[0,1]
	v_pk_mul_f32 v[46:47], v[62:63], v[42:43] op_sel_hi:[0,1]
	v_pk_mul_f32 v[42:43], v[6:7], v[40:41]
	v_pk_mul_f32 v[40:41], v[4:5], v[44:45]
	v_pk_mul_f32 v[46:47], v[2:3], v[46:47]
	v_pk_mul_f32 v[44:45], v[0:1], v[48:49]
	global_store_dwordx4 v[52:53], v[40:43], off offset:512
	global_store_dwordx4 v[52:53], v[44:47], off offset:528
	s_nop 1
	v_mov_b32_e32 v40, v172
	v_mov_b32_e32 v41, v173
	v_mov_b32_e32 v42, v174
	v_mov_b32_e32 v43, v175
	s_nop 0
	s_nop 1
	v_mov_b32_e32 v44, v176
	v_mov_b32_e32 v45, v177
	v_mov_b32_e32 v46, v178
	v_mov_b32_e32 v47, v179
	s_nop 1
	v_mov_b32_e32 v48, v108
	v_mov_b32_e32 v49, v109
	v_mov_b32_e32 v50, v110
	v_mov_b32_e32 v51, v111
	v_mov_b32_e32 v52, v40
	v_mov_b32_e32 v53, v44
	v_mov_b32_e32 v44, v41
	v_mov_b32_e32 v40, v42
	v_mov_b32_e32 v41, v46
	v_mov_b32_e32 v46, v43
	v_pk_add_f32 v[44:45], v[52:53], v[44:45]
	v_pk_add_f32 v[40:41], v[40:41], v[46:47]
	v_cvt_f32_f16_e32 v42, v48
	v_pk_add_f32 v[40:41], v[44:45], v[40:41]
	v_cvt_f32_f16_sdwa v43, v48 dst_sel:DWORD dst_unused:UNUSED_PAD src0_sel:WORD_1
	v_add_f32_e32 v21, v40, v41
	v_fmamk_f32 v21, v21, 0x3a000000, v38
	v_cvt_f32_f16_e32 v48, v49
	v_cvt_f32_f16_sdwa v49, v49 dst_sel:DWORD dst_unused:UNUSED_PAD src0_sel:WORD_1
	v_rsq_f32_e32 v52, v21
	v_cvt_f32_f16_e32 v62, v50
	v_cvt_f32_f16_sdwa v63, v50 dst_sel:DWORD dst_unused:UNUSED_PAD src0_sel:WORD_1
	v_cvt_f32_f16_e32 v50, v51
	v_cvt_f32_f16_sdwa v51, v51 dst_sel:DWORD dst_unused:UNUSED_PAD src0_sel:WORD_1
	v_pk_mul_f32 v[40:41], v[42:43], v[52:53] op_sel_hi:[1,0]
	v_pk_mul_f32 v[42:43], v[48:49], v[52:53] op_sel_hi:[1,0]
	v_pk_mul_f32 v[44:45], v[62:63], v[52:53] op_sel_hi:[1,0]
	v_pk_mul_f32 v[46:47], v[50:51], v[52:53] op_sel_hi:[1,0]
	v_pk_mul_f32 v[42:43], v[14:15], v[42:43]
	v_pk_mul_f32 v[40:41], v[12:13], v[40:41]
	v_pk_mul_f32 v[46:47], v[10:11], v[46:47]
	v_pk_mul_f32 v[44:45], v[8:9], v[44:45]
	global_store_dwordx4 v[68:69], v[40:43], off
	global_store_dwordx4 v[68:69], v[44:47], off offset:16
	s_nop 1
	v_mov_b32_e32 v40, v112
	v_mov_b32_e32 v41, v113
	v_mov_b32_e32 v42, v114
	v_mov_b32_e32 v43, v115
	v_cvt_f32_f16_e32 v44, v40
	v_cvt_f32_f16_sdwa v45, v40 dst_sel:DWORD dst_unused:UNUSED_PAD src0_sel:WORD_1
	v_cvt_f32_f16_e32 v40, v41
	v_cvt_f32_f16_sdwa v41, v41 dst_sel:DWORD dst_unused:UNUSED_PAD src0_sel:WORD_1
	v_cvt_f32_f16_e32 v46, v42
	v_cvt_f32_f16_sdwa v47, v42 dst_sel:DWORD dst_unused:UNUSED_PAD src0_sel:WORD_1
	v_cvt_f32_f16_e32 v42, v43
	v_cvt_f32_f16_sdwa v43, v43 dst_sel:DWORD dst_unused:UNUSED_PAD src0_sel:WORD_1
	v_pk_mul_f32 v[44:45], v[52:53], v[44:45] op_sel_hi:[0,1]
	v_pk_mul_f32 v[40:41], v[52:53], v[40:41] op_sel_hi:[0,1]
	v_pk_mul_f32 v[48:49], v[52:53], v[46:47] op_sel_hi:[0,1]
	v_pk_mul_f32 v[46:47], v[52:53], v[42:43] op_sel_hi:[0,1]
	v_pk_mul_f32 v[42:43], v[6:7], v[40:41]
	v_pk_mul_f32 v[40:41], v[4:5], v[44:45]
	v_pk_mul_f32 v[46:47], v[2:3], v[46:47]
	v_pk_mul_f32 v[44:45], v[0:1], v[48:49]
	global_store_dwordx4 v[68:69], v[40:43], off offset:512
	global_store_dwordx4 v[68:69], v[44:47], off offset:528
	s_nop 1
	v_mov_b32_e32 v40, v180
	v_mov_b32_e32 v41, v181
	v_mov_b32_e32 v42, v182
	v_mov_b32_e32 v43, v183
	s_nop 0
	s_nop 1
	v_mov_b32_e32 v44, v184
	v_mov_b32_e32 v45, v185
	v_mov_b32_e32 v46, v186
	v_mov_b32_e32 v47, v187
	s_nop 1
	v_mov_b32_e32 v48, v116
	v_mov_b32_e32 v49, v117
	v_mov_b32_e32 v50, v118
	v_mov_b32_e32 v51, v119
	v_mov_b32_e32 v52, v40
	v_mov_b32_e32 v53, v44
	v_mov_b32_e32 v44, v41
	v_mov_b32_e32 v40, v42
	v_mov_b32_e32 v41, v46
	v_mov_b32_e32 v46, v43
	v_pk_add_f32 v[44:45], v[52:53], v[44:45]
	v_pk_add_f32 v[40:41], v[40:41], v[46:47]
; #define GAS __attribute__((address_space(1)))
; __device__ __forceinline__ float bf_lo(unsigned w) { return __uint_as_float(w << 16); }
; __device__ __forceinline__ float bf_hi(unsigned w) { return __uint_as_float(w & 0xffff0000u); }
; __device__ __forceinline__ float rowss_sum(const float* p8) { const f32x4 a = *(const GAS f32x4*)((const GAS float*)p8), b = *(const GAS f32x4*)((const GAS float*)p8 + 4); return ((a[0] + a[1]) + (a[2] + a[3])) + ((b[0] + b[1]) + (b[2] + b[3])); }
; __device__ __forceinline__ void phase_final(const float* X, const float* rowss, const float* g, float* out, int grp, int rank, int H, int wv) {
;     ...
;         for (int h = 0; h < 2; ++h)
; #pragma unroll
;             for (int m = 0; m < 4; ++m) {
;                 const int row = row0 + h * 128 + m * 16;
;                 const float rs = __builtin_amdgcn_rsqf(rowss_sum(rowss + (size_t)row * 8) * INV_D + EPS);
;                 GAS float* orow = (GAS float*)out + (size_t)row * D + col0;
; #pragma unroll
;                 for (int bj = 0; bj < 2; ++bj) {
;     ...
;                     const u32x4 q = *(const GAS u32x4*)(xb + (size_t)((h * 4 + m) * 2 + bj) * 1024);
;                     f32x4 v0, v1;
;                     if (X_BF16 == 2) x20_unpack(q, *(const GAS unsigned*)((const GAS char*)X + (WS_XL - WS_X) + ((size_t)(u.pm * 8 + u.pn) * 8 + wid) * 4096 + (size_t)((h * 4 + m) * 2 + bj) * 256 + lane * 4), v0, v1);
;                     else if (X_BF16 == 3) xh_unpack(q, v0, v1);
;                     else { v0 = (f32x4){bf_lo(q.x), bf_hi(q.x), bf_lo(q.y), bf_hi(q.y)}; v1 = (f32x4){bf_lo(q.z), bf_hi(q.z), bf_lo(q.w), bf_hi(q.w)}; }
;                     *(GAS f32x4*)(orow + bj * 128) = v0 * rs * gv[bj][0]; *(GAS f32x4*)(orow + bj * 128 + 4) = v1 * rs * gv[bj][1];
	v_cvt_f32_f16_e32 v42, v48
	v_pk_add_f32 v[40:41], v[44:45], v[40:41]
	v_cvt_f32_f16_sdwa v43, v48 dst_sel:DWORD dst_unused:UNUSED_PAD src0_sel:WORD_1
	v_add_f32_e32 v21, v40, v41
	v_fmamk_f32 v21, v21, 0x3a000000, v38
	v_cvt_f32_f16_e32 v48, v49
	v_cvt_f32_f16_sdwa v49, v49 dst_sel:DWORD dst_unused:UNUSED_PAD src0_sel:WORD_1
	v_rsq_f32_e32 v52, v21
	v_cvt_f32_f16_e32 v62, v50
	v_cvt_f32_f16_sdwa v63, v50 dst_sel:DWORD dst_unused:UNUSED_PAD src0_sel:WORD_1
	v_cvt_f32_f16_e32 v50, v51
	v_cvt_f32_f16_sdwa v51, v51 dst_sel:DWORD dst_unused:UNUSED_PAD src0_sel:WORD_1
	v_pk_mul_f32 v[40:41], v[42:43], v[52:53] op_sel_hi:[1,0]
	v_pk_mul_f32 v[42:43], v[48:49], v[52:53] op_sel_hi:[1,0]
	v_pk_mul_f32 v[44:45], v[62:63], v[52:53] op_sel_hi:[1,0]
	v_pk_mul_f32 v[46:47], v[50:51], v[52:53] op_sel_hi:[1,0]
	v_pk_mul_f32 v[42:43], v[14:15], v[42:43]
	v_pk_mul_f32 v[40:41], v[12:13], v[40:41]
	v_pk_mul_f32 v[46:47], v[10:11], v[46:47]
	v_pk_mul_f32 v[44:45], v[8:9], v[44:45]
	global_store_dwordx4 v[54:55], v[40:43], off
	global_store_dwordx4 v[54:55], v[44:47], off offset:16
	s_nop 1
	v_mov_b32_e32 v40, v120
	v_mov_b32_e32 v41, v121
	v_mov_b32_e32 v42, v122
	v_mov_b32_e32 v43, v123
	v_cvt_f32_f16_e32 v44, v40
	v_cvt_f32_f16_sdwa v45, v40 dst_sel:DWORD dst_unused:UNUSED_PAD src0_sel:WORD_1
	v_cvt_f32_f16_e32 v40, v41
	v_cvt_f32_f16_sdwa v41, v41 dst_sel:DWORD dst_unused:UNUSED_PAD src0_sel:WORD_1
	v_cvt_f32_f16_e32 v46, v42
	v_cvt_f32_f16_sdwa v47, v42 dst_sel:DWORD dst_unused:UNUSED_PAD src0_sel:WORD_1
	v_cvt_f32_f16_e32 v42, v43
	v_cvt_f32_f16_sdwa v43, v43 dst_sel:DWORD dst_unused:UNUSED_PAD src0_sel:WORD_1
	v_pk_mul_f32 v[44:45], v[52:53], v[44:45] op_sel_hi:[0,1]
	v_pk_mul_f32 v[40:41], v[52:53], v[40:41] op_sel_hi:[0,1]
	v_pk_mul_f32 v[48:49], v[52:53], v[46:47] op_sel_hi:[0,1]
	v_pk_mul_f32 v[46:47], v[52:53], v[42:43] op_sel_hi:[0,1]
	v_pk_mul_f32 v[42:43], v[6:7], v[40:41]
	v_pk_mul_f32 v[40:41], v[4:5], v[44:45]
	v_pk_mul_f32 v[46:47], v[2:3], v[46:47]
	v_pk_mul_f32 v[44:45], v[0:1], v[48:49]
	global_store_dwordx4 v[54:55], v[40:43], off offset:512
	global_store_dwordx4 v[54:55], v[44:47], off offset:528
	s_nop 1
	v_mov_b32_e32 v40, v188
	v_mov_b32_e32 v41, v189
	v_mov_b32_e32 v42, v190
	v_mov_b32_e32 v43, v191
	s_nop 0
	s_nop 1
	v_mov_b32_e32 v44, v192
	v_mov_b32_e32 v45, v193
	v_mov_b32_e32 v46, v194
	v_mov_b32_e32 v47, v195
	s_nop 1
	v_mov_b32_e32 v48, v124
	v_mov_b32_e32 v49, v125
	v_mov_b32_e32 v50, v126
	v_mov_b32_e32 v51, v127
	v_mov_b32_e32 v52, v40
	v_mov_b32_e32 v53, v44
	v_mov_b32_e32 v44, v41
	v_mov_b32_e32 v40, v42
	v_mov_b32_e32 v41, v46
	v_mov_b32_e32 v46, v43
	v_pk_add_f32 v[44:45], v[52:53], v[44:45]
	v_pk_add_f32 v[40:41], v[40:41], v[46:47]
	v_cvt_f32_f16_e32 v42, v48
	v_pk_add_f32 v[40:41], v[44:45], v[40:41]
	v_cvt_f32_f16_sdwa v43, v48 dst_sel:DWORD dst_unused:UNUSED_PAD src0_sel:WORD_1
	v_add_f32_e32 v21, v40, v41
	v_fmamk_f32 v21, v21, 0x3a000000, v38
	v_cvt_f32_f16_e32 v48, v49
	v_cvt_f32_f16_sdwa v49, v49 dst_sel:DWORD dst_unused:UNUSED_PAD src0_sel:WORD_1
	v_rsq_f32_e32 v52, v21
	v_cvt_f32_f16_e32 v54, v50
	v_cvt_f32_f16_sdwa v55, v50 dst_sel:DWORD dst_unused:UNUSED_PAD src0_sel:WORD_1
	v_cvt_f32_f16_e32 v50, v51
	v_cvt_f32_f16_sdwa v51, v51 dst_sel:DWORD dst_unused:UNUSED_PAD src0_sel:WORD_1
	v_pk_mul_f32 v[40:41], v[42:43], v[52:53] op_sel_hi:[1,0]
	v_pk_mul_f32 v[42:43], v[48:49], v[52:53] op_sel_hi:[1,0]
	v_pk_mul_f32 v[44:45], v[54:55], v[52:53] op_sel_hi:[1,0]
	v_pk_mul_f32 v[46:47], v[50:51], v[52:53] op_sel_hi:[1,0]
	v_pk_mul_f32 v[42:43], v[14:15], v[42:43]
	v_pk_mul_f32 v[40:41], v[12:13], v[40:41]
	v_pk_mul_f32 v[46:47], v[10:11], v[46:47]
	v_pk_mul_f32 v[44:45], v[8:9], v[44:45]
	global_store_dwordx4 v[72:73], v[40:43], off
	global_store_dwordx4 v[72:73], v[44:47], off offset:16
	s_nop 1
	v_mov_b32_e32 v40, v128
	v_mov_b32_e32 v41, v129
	v_mov_b32_e32 v42, v130
	v_mov_b32_e32 v43, v131
	v_cvt_f32_f16_e32 v44, v40
	v_cvt_f32_f16_sdwa v45, v40 dst_sel:DWORD dst_unused:UNUSED_PAD src0_sel:WORD_1
	v_cvt_f32_f16_e32 v40, v41
	v_cvt_f32_f16_sdwa v41, v41 dst_sel:DWORD dst_unused:UNUSED_PAD src0_sel:WORD_1
	v_cvt_f32_f16_e32 v46, v42
	v_cvt_f32_f16_sdwa v47, v42 dst_sel:DWORD dst_unused:UNUSED_PAD src0_sel:WORD_1
	v_cvt_f32_f16_e32 v42, v43
	v_cvt_f32_f16_sdwa v43, v43 dst_sel:DWORD dst_unused:UNUSED_PAD src0_sel:WORD_1
	v_pk_mul_f32 v[44:45], v[52:53], v[44:45] op_sel_hi:[0,1]
	v_pk_mul_f32 v[40:41], v[52:53], v[40:41] op_sel_hi:[0,1]
	v_pk_mul_f32 v[48:49], v[52:53], v[46:47] op_sel_hi:[0,1]
	v_pk_mul_f32 v[46:47], v[52:53], v[42:43] op_sel_hi:[0,1]
	v_pk_mul_f32 v[42:43], v[6:7], v[40:41]
	v_pk_mul_f32 v[40:41], v[4:5], v[44:45]
	v_pk_mul_f32 v[46:47], v[2:3], v[46:47]
	v_pk_mul_f32 v[44:45], v[0:1], v[48:49]
	global_store_dwordx4 v[72:73], v[40:43], off offset:512
	global_store_dwordx4 v[72:73], v[44:47], off offset:528
	s_nop 1
	v_mov_b32_e32 v40, v196
	v_mov_b32_e32 v41, v197
	v_mov_b32_e32 v42, v198
	v_mov_b32_e32 v43, v199
	s_nop 0
	s_nop 1
	v_mov_b32_e32 v44, v200
	v_mov_b32_e32 v45, v201
	v_mov_b32_e32 v46, v202
	v_mov_b32_e32 v47, v203
	s_nop 1
	v_mov_b32_e32 v48, v132
	v_mov_b32_e32 v49, v133
	v_mov_b32_e32 v50, v134
	v_mov_b32_e32 v51, v135
	v_mov_b32_e32 v52, v40
	v_mov_b32_e32 v53, v44
	v_mov_b32_e32 v44, v41
	v_mov_b32_e32 v40, v42
	v_mov_b32_e32 v41, v46
	v_mov_b32_e32 v46, v43
	v_pk_add_f32 v[44:45], v[52:53], v[44:45]
	v_pk_add_f32 v[40:41], v[40:41], v[46:47]
	v_cvt_f32_f16_e32 v42, v48
	v_pk_add_f32 v[40:41], v[44:45], v[40:41]
	v_cvt_f32_f16_sdwa v43, v48 dst_sel:DWORD dst_unused:UNUSED_PAD src0_sel:WORD_1
	v_add_f32_e32 v21, v40, v41
	v_fmamk_f32 v21, v21, 0x3a000000, v38
; #define GAS __attribute__((address_space(1)))
; __device__ __forceinline__ float bf_lo(unsigned w) { return __uint_as_float(w << 16); }
; __device__ __forceinline__ float bf_hi(unsigned w) { return __uint_as_float(w & 0xffff0000u); }
; __device__ __forceinline__ float rowss_sum(const float* p8) { const f32x4 a = *(const GAS f32x4*)((const GAS float*)p8), b = *(const GAS f32x4*)((const GAS float*)p8 + 4); return ((a[0] + a[1]) + (a[2] + a[3])) + ((b[0] + b[1]) + (b[2] + b[3])); }
; __device__ __forceinline__ void phase_final(const float* X, const float* rowss, const float* g, float* out, int grp, int rank, int H, int wv) {
;     ...
;         for (int h = 0; h < 2; ++h)
; #pragma unroll
;             for (int m = 0; m < 4; ++m) {
;                 const int row = row0 + h * 128 + m * 16;
;                 const float rs = __builtin_amdgcn_rsqf(rowss_sum(rowss + (size_t)row * 8) * INV_D + EPS);
;                 GAS float* orow = (GAS float*)out + (size_t)row * D + col0;
; #pragma unroll
;                 for (int bj = 0; bj < 2; ++bj) {
;     ...
;                     const u32x4 q = *(const GAS u32x4*)(xb + (size_t)((h * 4 + m) * 2 + bj) * 1024);
;                     f32x4 v0, v1;
;                     if (X_BF16 == 2) x20_unpack(q, *(const GAS unsigned*)((const GAS char*)X + (WS_XL - WS_X) + ((size_t)(u.pm * 8 + u.pn) * 8 + wid) * 4096 + (size_t)((h * 4 + m) * 2 + bj) * 256 + lane * 4), v0, v1);
;                     else if (X_BF16 == 3) xh_unpack(q, v0, v1);
;                     else { v0 = (f32x4){bf_lo(q.x), bf_hi(q.x), bf_lo(q.y), bf_hi(q.y)}; v1 = (f32x4){bf_lo(q.z), bf_hi(q.z), bf_lo(q.w), bf_hi(q.w)}; }
;                     *(GAS f32x4*)(orow + bj * 128) = v0 * rs * gv[bj][0]; *(GAS f32x4*)(orow + bj * 128 + 4) = v1 * rs * gv[bj][1];
	v_cvt_f32_f16_e32 v48, v49
	v_cvt_f32_f16_sdwa v49, v49 dst_sel:DWORD dst_unused:UNUSED_PAD src0_sel:WORD_1
	v_rsq_f32_e32 v52, v21
	v_cvt_f32_f16_e32 v54, v50
	v_cvt_f32_f16_sdwa v55, v50 dst_sel:DWORD dst_unused:UNUSED_PAD src0_sel:WORD_1
	v_cvt_f32_f16_e32 v50, v51
	v_cvt_f32_f16_sdwa v51, v51 dst_sel:DWORD dst_unused:UNUSED_PAD src0_sel:WORD_1
	v_pk_mul_f32 v[40:41], v[42:43], v[52:53] op_sel_hi:[1,0]
	v_pk_mul_f32 v[42:43], v[48:49], v[52:53] op_sel_hi:[1,0]
	v_pk_mul_f32 v[44:45], v[54:55], v[52:53] op_sel_hi:[1,0]
	v_pk_mul_f32 v[46:47], v[50:51], v[52:53] op_sel_hi:[1,0]
	v_pk_mul_f32 v[42:43], v[14:15], v[42:43]
	v_pk_mul_f32 v[40:41], v[12:13], v[40:41]
	v_pk_mul_f32 v[46:47], v[10:11], v[46:47]
	v_pk_mul_f32 v[44:45], v[8:9], v[44:45]
	global_store_dwordx4 v[34:35], v[40:43], off
	global_store_dwordx4 v[34:35], v[44:47], off offset:16
	s_nop 1
	v_mov_b32_e32 v40, v136
	v_mov_b32_e32 v41, v137
	v_mov_b32_e32 v42, v138
	v_mov_b32_e32 v43, v139
	v_cvt_f32_f16_e32 v44, v40
	v_cvt_f32_f16_sdwa v45, v40 dst_sel:DWORD dst_unused:UNUSED_PAD src0_sel:WORD_1
	v_cvt_f32_f16_e32 v40, v41
	v_cvt_f32_f16_sdwa v41, v41 dst_sel:DWORD dst_unused:UNUSED_PAD src0_sel:WORD_1
	v_cvt_f32_f16_e32 v46, v42
	v_cvt_f32_f16_sdwa v47, v42 dst_sel:DWORD dst_unused:UNUSED_PAD src0_sel:WORD_1
	v_cvt_f32_f16_e32 v42, v43
	v_cvt_f32_f16_sdwa v43, v43 dst_sel:DWORD dst_unused:UNUSED_PAD src0_sel:WORD_1
	v_pk_mul_f32 v[44:45], v[52:53], v[44:45] op_sel_hi:[0,1]
	v_pk_mul_f32 v[40:41], v[52:53], v[40:41] op_sel_hi:[0,1]
	v_pk_mul_f32 v[48:49], v[52:53], v[46:47] op_sel_hi:[0,1]
	v_pk_mul_f32 v[46:47], v[52:53], v[42:43] op_sel_hi:[0,1]
	v_pk_mul_f32 v[42:43], v[6:7], v[40:41]
	v_pk_mul_f32 v[40:41], v[4:5], v[44:45]
	v_pk_mul_f32 v[46:47], v[2:3], v[46:47]
	v_pk_mul_f32 v[44:45], v[0:1], v[48:49]
	global_store_dwordx4 v[34:35], v[40:43], off offset:512
	global_store_dwordx4 v[34:35], v[44:47], off offset:528
	s_nop 1
	v_mov_b32_e32 v40, v204
	v_mov_b32_e32 v41, v205
	v_mov_b32_e32 v42, v206
	v_mov_b32_e32 v43, v207
	s_nop 0
	s_nop 1
	v_mov_b32_e32 v44, v208
	v_mov_b32_e32 v45, v209
	v_mov_b32_e32 v46, v210
	v_mov_b32_e32 v47, v211
	s_nop 1
	v_mov_b32_e32 v48, v140
	v_mov_b32_e32 v49, v141
	v_mov_b32_e32 v50, v142
	v_mov_b32_e32 v51, v143
	v_mov_b32_e32 v32, v40
	v_mov_b32_e32 v33, v44
	v_mov_b32_e32 v44, v41
	v_mov_b32_e32 v34, v42
	v_mov_b32_e32 v35, v46
	v_mov_b32_e32 v46, v43
	v_pk_add_f32 v[32:33], v[32:33], v[44:45]
	v_pk_add_f32 v[34:35], v[34:35], v[46:47]
	v_cvt_f32_f16_e32 v40, v48
	v_pk_add_f32 v[32:33], v[32:33], v[34:35]
	v_cvt_f32_f16_sdwa v41, v48 dst_sel:DWORD dst_unused:UNUSED_PAD src0_sel:WORD_1
	v_add_f32_e32 v21, v32, v33
	v_fmamk_f32 v21, v21, 0x3a000000, v38
	v_cvt_f32_f16_e32 v42, v49
	v_cvt_f32_f16_sdwa v43, v49 dst_sel:DWORD dst_unused:UNUSED_PAD src0_sel:WORD_1
	v_rsq_f32_e32 v44, v21
	v_cvt_f32_f16_e32 v48, v50
	v_cvt_f32_f16_sdwa v49, v50 dst_sel:DWORD dst_unused:UNUSED_PAD src0_sel:WORD_1
	v_cvt_f32_f16_e32 v50, v51
	v_cvt_f32_f16_sdwa v51, v51 dst_sel:DWORD dst_unused:UNUSED_PAD src0_sel:WORD_1
	v_pk_mul_f32 v[32:33], v[40:41], v[44:45] op_sel_hi:[1,0]
	v_pk_mul_f32 v[34:35], v[42:43], v[44:45] op_sel_hi:[1,0]
	v_pk_mul_f32 v[40:41], v[48:49], v[44:45] op_sel_hi:[1,0]
	v_pk_mul_f32 v[42:43], v[50:51], v[44:45] op_sel_hi:[1,0]
	v_pk_mul_f32 v[34:35], v[14:15], v[34:35]
	v_pk_mul_f32 v[32:33], v[12:13], v[32:33]
	v_pk_mul_f32 v[42:43], v[10:11], v[42:43]
	v_pk_mul_f32 v[40:41], v[8:9], v[40:41]
	global_store_dwordx4 v[24:25], v[32:35], off
	global_store_dwordx4 v[24:25], v[40:43], off offset:16
	s_nop 1
	v_mov_b32_e32 v30, v144
	v_mov_b32_e32 v31, v145
	v_mov_b32_e32 v32, v146
	v_mov_b32_e32 v33, v147
	v_add_co_u32_e32 v34, vcc, s11, v26
	v_cvt_f32_f16_e32 v26, v30
	v_addc_co_u32_e32 v35, vcc, 0, v27, vcc
	v_cvt_f32_f16_sdwa v27, v30 dst_sel:DWORD dst_unused:UNUSED_PAD src0_sel:WORD_1
	v_cvt_f32_f16_e32 v30, v31
	v_cvt_f32_f16_sdwa v31, v31 dst_sel:DWORD dst_unused:UNUSED_PAD src0_sel:WORD_1
	v_cvt_f32_f16_e32 v40, v32
	v_cvt_f32_f16_sdwa v41, v32 dst_sel:DWORD dst_unused:UNUSED_PAD src0_sel:WORD_1
	v_cvt_f32_f16_e32 v32, v33
	v_cvt_f32_f16_sdwa v33, v33 dst_sel:DWORD dst_unused:UNUSED_PAD src0_sel:WORD_1
	v_pk_mul_f32 v[26:27], v[44:45], v[26:27] op_sel_hi:[0,1]
	v_pk_mul_f32 v[30:31], v[44:45], v[30:31] op_sel_hi:[0,1]
	v_pk_mul_f32 v[40:41], v[44:45], v[40:41] op_sel_hi:[0,1]
	v_pk_mul_f32 v[42:43], v[44:45], v[32:33] op_sel_hi:[0,1]
	v_pk_mul_f32 v[32:33], v[6:7], v[30:31]
	v_pk_mul_f32 v[30:31], v[4:5], v[26:27]
	v_pk_mul_f32 v[42:43], v[2:3], v[42:43]
	v_pk_mul_f32 v[40:41], v[0:1], v[40:41]
	global_store_dwordx4 v[24:25], v[30:33], off offset:512
	global_store_dwordx4 v[24:25], v[40:43], off offset:528
	s_nop 1
	v_mov_b32_e32 v24, v212
	v_mov_b32_e32 v25, v213
	v_mov_b32_e32 v26, v214
	v_mov_b32_e32 v27, v215
	s_nop 0
	s_nop 1
	v_mov_b32_e32 v30, v216
	v_mov_b32_e32 v31, v217
	v_mov_b32_e32 v32, v218
	v_mov_b32_e32 v33, v219
	s_nop 1
	v_mov_b32_e32 v40, v148
	v_mov_b32_e32 v41, v149
	v_mov_b32_e32 v42, v150
	v_mov_b32_e32 v43, v151
	v_lshlrev_b64 v[22:23], 13, v[28:29]
	v_lshl_add_u64 v[44:45], v[18:19], 0, v[22:23]
	v_mov_b32_e32 v22, v24
	v_mov_b32_e32 v23, v30
	v_mov_b32_e32 v30, v25
	v_mov_b32_e32 v24, v26
; #define GAS __attribute__((address_space(1)))
; __device__ __forceinline__ float bf_lo(unsigned w) { return __uint_as_float(w << 16); }
; __device__ __forceinline__ float bf_hi(unsigned w) { return __uint_as_float(w & 0xffff0000u); }
; __device__ __forceinline__ float rowss_sum(const float* p8) { const f32x4 a = *(const GAS f32x4*)((const GAS float*)p8), b = *(const GAS f32x4*)((const GAS float*)p8 + 4); return ((a[0] + a[1]) + (a[2] + a[3])) + ((b[0] + b[1]) + (b[2] + b[3])); }
; __device__ __forceinline__ void phase_final(const float* X, const float* rowss, const float* g, float* out, int grp, int rank, int H, int wv) {
;     ...
;         for (int h = 0; h < 2; ++h)
; #pragma unroll
;             for (int m = 0; m < 4; ++m) {
;                 const int row = row0 + h * 128 + m * 16;
;                 const float rs = __builtin_amdgcn_rsqf(rowss_sum(rowss + (size_t)row * 8) * INV_D + EPS);
;                 GAS float* orow = (GAS float*)out + (size_t)row * D + col0;
; #pragma unroll
;                 for (int bj = 0; bj < 2; ++bj) {
;     ...
;                     const u32x4 q = *(const GAS u32x4*)(xb + (size_t)((h * 4 + m) * 2 + bj) * 1024);
;                     f32x4 v0, v1;
;                     if (X_BF16 == 2) x20_unpack(q, *(const GAS unsigned*)((const GAS char*)X + (WS_XL - WS_X) + ((size_t)(u.pm * 8 + u.pn) * 8 + wid) * 4096 + (size_t)((h * 4 + m) * 2 + bj) * 256 + lane * 4), v0, v1);
;                     else if (X_BF16 == 3) xh_unpack(q, v0, v1);
;                     else { v0 = (f32x4){bf_lo(q.x), bf_hi(q.x), bf_lo(q.y), bf_hi(q.y)}; v1 = (f32x4){bf_lo(q.z), bf_hi(q.z), bf_lo(q.w), bf_hi(q.w)}; }
;                     *(GAS f32x4*)(orow + bj * 128) = v0 * rs * gv[bj][0]; *(GAS f32x4*)(orow + bj * 128 + 4) = v1 * rs * gv[bj][1];
	v_mov_b32_e32 v25, v32
	v_mov_b32_e32 v32, v27
	v_pk_add_f32 v[22:23], v[22:23], v[30:31]
	v_pk_add_f32 v[24:25], v[24:25], v[32:33]
	v_cvt_f32_f16_e32 v26, v40
	v_pk_add_f32 v[22:23], v[22:23], v[24:25]
	v_cvt_f32_f16_sdwa v27, v40 dst_sel:DWORD dst_unused:UNUSED_PAD src0_sel:WORD_1
	v_add_f32_e32 v21, v22, v23
	v_fmamk_f32 v21, v21, 0x3a000000, v38
	v_cvt_f32_f16_e32 v28, v41
	v_cvt_f32_f16_sdwa v29, v41 dst_sel:DWORD dst_unused:UNUSED_PAD src0_sel:WORD_1
	v_rsq_f32_e32 v30, v21
	v_cvt_f32_f16_e32 v40, v42
	v_cvt_f32_f16_sdwa v41, v42 dst_sel:DWORD dst_unused:UNUSED_PAD src0_sel:WORD_1
	v_cvt_f32_f16_e32 v42, v43
	v_cvt_f32_f16_sdwa v43, v43 dst_sel:DWORD dst_unused:UNUSED_PAD src0_sel:WORD_1
	v_pk_mul_f32 v[22:23], v[26:27], v[30:31] op_sel_hi:[1,0]
	v_pk_mul_f32 v[24:25], v[28:29], v[30:31] op_sel_hi:[1,0]
	v_pk_mul_f32 v[26:27], v[40:41], v[30:31] op_sel_hi:[1,0]
	v_pk_mul_f32 v[28:29], v[42:43], v[30:31] op_sel_hi:[1,0]
	v_pk_mul_f32 v[24:25], v[14:15], v[24:25]
	v_pk_mul_f32 v[22:23], v[12:13], v[22:23]
	v_pk_mul_f32 v[28:29], v[10:11], v[28:29]
	v_pk_mul_f32 v[26:27], v[8:9], v[26:27]
	global_store_dwordx4 v[44:45], v[22:25], off
	global_store_dwordx4 v[44:45], v[26:29], off offset:16
	s_nop 1
	v_mov_b32_e32 v22, v152
	v_mov_b32_e32 v23, v153
	v_mov_b32_e32 v24, v154
	v_mov_b32_e32 v25, v155
	v_add_u32_e32 v32, 0xb0, v20
	v_ashrrev_i32_e32 v33, 31, v32
	v_lshlrev_b64 v[20:21], 5, v[32:33]
	v_lshl_add_u64 v[40:41], s[4:5], 0, v[20:21]
	v_lshlrev_b64 v[32:33], 13, v[32:33]
	v_lshl_add_u64 v[18:19], v[18:19], 0, v[32:33]
	v_cvt_f32_f16_e32 v20, v22
	v_cvt_f32_f16_sdwa v21, v22 dst_sel:DWORD dst_unused:UNUSED_PAD src0_sel:WORD_1
	v_cvt_f32_f16_e32 v22, v23
	v_cvt_f32_f16_sdwa v23, v23 dst_sel:DWORD dst_unused:UNUSED_PAD src0_sel:WORD_1
	v_cvt_f32_f16_e32 v26, v24
	v_cvt_f32_f16_sdwa v27, v24 dst_sel:DWORD dst_unused:UNUSED_PAD src0_sel:WORD_1
	v_cvt_f32_f16_e32 v24, v25
	v_cvt_f32_f16_sdwa v25, v25 dst_sel:DWORD dst_unused:UNUSED_PAD src0_sel:WORD_1
	v_pk_mul_f32 v[20:21], v[30:31], v[20:21] op_sel_hi:[0,1]
	v_pk_mul_f32 v[22:23], v[30:31], v[22:23] op_sel_hi:[0,1]
	v_pk_mul_f32 v[28:29], v[30:31], v[26:27] op_sel_hi:[0,1]
	v_pk_mul_f32 v[24:25], v[30:31], v[24:25] op_sel_hi:[0,1]
	v_pk_mul_f32 v[22:23], v[6:7], v[22:23]
	v_pk_mul_f32 v[20:21], v[4:5], v[20:21]
	v_pk_mul_f32 v[26:27], v[2:3], v[24:25]
	v_pk_mul_f32 v[24:25], v[0:1], v[28:29]
	global_store_dwordx4 v[44:45], v[20:23], off offset:512
	global_store_dwordx4 v[44:45], v[24:27], off offset:528
	s_nop 1
	v_mov_b32_e32 v20, v220
	v_mov_b32_e32 v21, v221
	v_mov_b32_e32 v22, v222
	v_mov_b32_e32 v23, v223
	s_nop 0
	s_nop 1
	v_mov_b32_e32 v24, v224
	v_mov_b32_e32 v25, v225
	v_mov_b32_e32 v26, v226
	v_mov_b32_e32 v27, v227
	s_nop 1
	v_mov_b32_e32 v28, v156
	v_mov_b32_e32 v29, v157
	v_mov_b32_e32 v30, v158
	v_mov_b32_e32 v31, v159
	v_mov_b32_e32 v32, v20
	v_mov_b32_e32 v33, v24
	v_mov_b32_e32 v24, v21
	v_mov_b32_e32 v20, v22
	v_mov_b32_e32 v21, v26
	v_mov_b32_e32 v26, v23
	v_pk_add_f32 v[24:25], v[32:33], v[24:25]
	v_pk_add_f32 v[20:21], v[20:21], v[26:27]
	v_cvt_f32_f16_e32 v22, v28
	v_pk_add_f32 v[20:21], v[24:25], v[20:21]
	v_cvt_f32_f16_sdwa v23, v28 dst_sel:DWORD dst_unused:UNUSED_PAD src0_sel:WORD_1
	v_add_f32_e32 v20, v20, v21
	v_fmamk_f32 v20, v20, 0x3a000000, v38
	v_cvt_f32_f16_e32 v28, v29
	v_cvt_f32_f16_sdwa v29, v29 dst_sel:DWORD dst_unused:UNUSED_PAD src0_sel:WORD_1
	v_rsq_f32_e32 v20, v20
	v_cvt_f32_f16_e32 v40, v30
	v_cvt_f32_f16_sdwa v41, v30 dst_sel:DWORD dst_unused:UNUSED_PAD src0_sel:WORD_1
	v_cvt_f32_f16_e32 v30, v31
	v_cvt_f32_f16_sdwa v31, v31 dst_sel:DWORD dst_unused:UNUSED_PAD src0_sel:WORD_1
	v_pk_mul_f32 v[22:23], v[22:23], v[20:21] op_sel_hi:[1,0]
	v_pk_mul_f32 v[24:25], v[28:29], v[20:21] op_sel_hi:[1,0]
	v_pk_mul_f32 v[26:27], v[40:41], v[20:21] op_sel_hi:[1,0]
	v_pk_mul_f32 v[28:29], v[30:31], v[20:21] op_sel_hi:[1,0]
	v_pk_mul_f32 v[14:15], v[14:15], v[24:25]
	v_pk_mul_f32 v[12:13], v[12:13], v[22:23]
	v_pk_mul_f32 v[10:11], v[10:11], v[28:29]
	v_pk_mul_f32 v[8:9], v[8:9], v[26:27]
	global_store_dwordx4 v[18:19], v[12:15], off
	global_store_dwordx4 v[18:19], v[8:11], off offset:16
	s_nop 1
	v_mov_b32_e32 v8, v160
	v_mov_b32_e32 v9, v161
	v_mov_b32_e32 v10, v162
	v_mov_b32_e32 v11, v163
	v_cvt_f32_f16_e32 v12, v8
	v_cvt_f32_f16_sdwa v13, v8 dst_sel:DWORD dst_unused:UNUSED_PAD src0_sel:WORD_1
	v_cvt_f32_f16_e32 v8, v9
	v_cvt_f32_f16_sdwa v9, v9 dst_sel:DWORD dst_unused:UNUSED_PAD src0_sel:WORD_1
	v_cvt_f32_f16_e32 v14, v10
	v_cvt_f32_f16_sdwa v15, v10 dst_sel:DWORD dst_unused:UNUSED_PAD src0_sel:WORD_1
	v_cvt_f32_f16_e32 v10, v11
	v_cvt_f32_f16_sdwa v11, v11 dst_sel:DWORD dst_unused:UNUSED_PAD src0_sel:WORD_1
	v_pk_mul_f32 v[12:13], v[20:21], v[12:13] op_sel_hi:[0,1]
	v_pk_mul_f32 v[8:9], v[20:21], v[8:9] op_sel_hi:[0,1]
	v_pk_mul_f32 v[14:15], v[20:21], v[14:15] op_sel_hi:[0,1]
	v_pk_mul_f32 v[10:11], v[20:21], v[10:11] op_sel_hi:[0,1]
	v_pk_mul_f32 v[6:7], v[6:7], v[8:9]
	v_pk_mul_f32 v[4:5], v[4:5], v[12:13]
	v_pk_mul_f32 v[2:3], v[2:3], v[10:11]
	v_pk_mul_f32 v[0:1], v[0:1], v[14:15]
	global_store_dwordx4 v[18:19], v[4:7], off offset:512
	global_store_dwordx4 v[18:19], v[0:3], off offset:528
	s_cbranch_scc1 .LBB0_1446
